# residual-GEMM epilogue: ALIGN rendezvous of waves 0-3 moved below their first residual load batch so those loads overlap the other half's last MFMA section
# speedup vs baseline: 1.0001x; 1.0001x over previous
; #define PG8_STAGE(bufoff, gbase, voff) do { _Pragma("unroll") for (int _i = 0; _i < 2; ++_i) \
;         __builtin_amdgcn_global_load_lds((const unsigned*)((const char*)(gbase) + (voff)[_i]), (LAS unsigned*)(lds + (bufoff) + ldsw + _i * 8192), 16, 0, 0); } while (0)
; #define PG8_WAIT_V(n) asm volatile("s_waitcnt vmcnt(" #n ")" ::: "memory")
; #define PG8_WAIT_L(n) asm volatile("s_waitcnt lgkmcnt(" #n ")" ::: "memory")
; template <class Epi>
; __device__ __forceinline__ void gemm_phase(LAS unsigned char* lds, const Gemm g, const StaticOrder& S, const Epi& E, const int tid) {
;     ...
;     f32x4 acc[2][2][4][2];
; #pragma unroll
;     for (int a = 0; a < 2; ++a)
; #pragma unroll
;         for (int b = 0; b < 2; ++b)
; #pragma unroll
;             for (int m = 0; m < 4; ++m)
; #pragma unroll
;                 for (int n = 0; n < 2; ++n) acc[a][b][m][n] = (f32x4){0.f, 0.f, 0.f, 0.f};
;     bf16x8 At[4][2], B0[2][2], B1[2][2];
;     const char* cA = (const char*)g.A + (size_t)cur.pm * tstepA + (size_t)cur.pn * pnoffA; const char* cB = (const char*)g.Bt + (size_t)cur.pn * tstepB;
;     PG8_STAGE(PG8_SB(0, 0), cB, voffB); PG8_STAGE(PG8_SB(0, 1), cB + hstepB, voffB); PG8_STAGE(PG8_SA(0, 0), cA, voffA); PG8_STAGE(PG8_SA(0, 1), cA + hstepA, voffA);
;     if (wr == 1) PG8_BAR;
;     PG8_WAIT_V(2); PG8_BAR;
;     PG8_STAGE(PG8_SB(1, 0), cB + kstep, voffB); PG8_STAGE(PG8_SA(1, 0), cA + kstepA, voffA); PG8_STAGE(PG8_SB(1, 1), cB + hstepB + kstep, voffB);
;     PG8_WAIT_V(6); PG8_BAR;
;     for (;;) {
;         const bool has_next = S.next(ui + 1, nxt);
;         const char* nA = has_next ? (const char*)g.A + (size_t)nxt.pm * tstepA + (size_t)nxt.pn * pnoffA : cA; const char* nB = has_next ? (const char*)g.Bt + (size_t)nxt.pn * tstepB : cB;
;         for (int t = 0; t < nt; t += 2) {
;             const bool last = (t == nt - 2);
;             const char* a1 = cA + (size_t)(t + 1) * kstepA;
;             const char* a2 = last ? nA : cA + (size_t)(t + 2) * kstepA; const char* b2 = last ? nB : cB + (size_t)(t + 2) * kstep;
;             const char* a3 = a2 + kstepA; const char* b3 = b2 + kstep;
;             PG8_LDB(B0, 0, 0); PG8_LDB(B1, 0, 1); PG8_SCHED; PG8_LDA(At, 0, 0); PG8_STAGE(PG8_SA(1, 1), a1 + hstepA, voffA);
;             PG8_WAIT_V(8); PG8_WAIT_L(0); PG8_BAR; PG8_MMA(0, 0, At, B0); PG8_MMA(0, 1, At, B1); PG8_BAR; PG8_SCHED;
.LBB0_392:
	s_add_u32 s71, s2, s21
	s_addc_u32 s72, s3, 0
	s_add_u32 s73, s28, 0x100
	v_mov_b32_e32 v0, 0
	s_addc_u32 s75, s29, 0
	s_mov_b64 s[28:29], 0
	s_waitcnt lgkmcnt(0)
	v_mov_b64_e32 v[0:1], 0
	v_mov_b64_e32 v[2:3], 0
	v_mov_b64_e32 v[4:5], 0
	v_mov_b64_e32 v[6:7], 0
	v_mov_b64_e32 v[8:9], 0
	v_mov_b64_e32 v[10:11], 0
	v_mov_b64_e32 v[12:13], 0
	v_mov_b64_e32 v[14:15], 0
	v_mov_b64_e32 v[16:17], 0
	v_mov_b64_e32 v[18:19], 0
	v_mov_b64_e32 v[20:21], 0
	v_mov_b64_e32 v[22:23], 0
	v_mov_b64_e32 v[24:25], 0
	v_mov_b64_e32 v[26:27], 0
	v_mov_b64_e32 v[28:29], 0
	v_mov_b64_e32 v[30:31], 0
	v_mov_b64_e32 v[32:33], 0
	v_mov_b64_e32 v[34:35], 0
	v_mov_b64_e32 v[36:37], 0
	v_mov_b64_e32 v[38:39], 0
	v_mov_b64_e32 v[40:41], 0
	v_mov_b64_e32 v[42:43], 0
	v_mov_b64_e32 v[44:45], 0
	v_mov_b64_e32 v[46:47], 0
	v_mov_b64_e32 v[48:49], 0
	v_mov_b64_e32 v[50:51], 0
	v_mov_b64_e32 v[52:53], 0
	v_mov_b64_e32 v[54:55], 0
	v_mov_b64_e32 v[56:57], 0
	v_mov_b64_e32 v[58:59], 0
	v_mov_b64_e32 v[60:61], 0
	v_mov_b64_e32 v[62:63], 0
	v_mov_b64_e32 v[64:65], 0
	v_mov_b64_e32 v[66:67], 0
	v_mov_b64_e32 v[68:69], 0
	v_mov_b64_e32 v[70:71], 0
	v_mov_b64_e32 v[72:73], 0
	v_mov_b64_e32 v[74:75], 0
	v_mov_b64_e32 v[76:77], 0
	v_mov_b64_e32 v[78:79], 0
	v_mov_b64_e32 v[80:81], 0
	v_mov_b64_e32 v[82:83], 0
	v_mov_b64_e32 v[84:85], 0
	v_mov_b64_e32 v[86:87], 0
	v_mov_b64_e32 v[88:89], 0
	v_mov_b64_e32 v[90:91], 0
	v_mov_b64_e32 v[92:93], 0
	v_mov_b64_e32 v[94:95], 0
	v_mov_b64_e32 v[96:97], 0
	v_mov_b64_e32 v[98:99], 0
	v_mov_b64_e32 v[100:101], 0
	v_mov_b64_e32 v[102:103], 0
	v_mov_b64_e32 v[104:105], 0
	v_mov_b64_e32 v[106:107], 0
	v_mov_b64_e32 v[108:109], 0
	v_mov_b64_e32 v[110:111], 0
	v_mov_b64_e32 v[112:113], 0
	v_mov_b64_e32 v[114:115], 0
	v_mov_b64_e32 v[116:117], 0
	v_mov_b64_e32 v[118:119], 0
	v_mov_b64_e32 v[120:121], 0
	v_mov_b64_e32 v[122:123], 0
	v_mov_b64_e32 v[132:133], 0
	v_mov_b64_e32 v[134:135], 0
.LBB0_393:
	s_add_u32 s80, s28, 1
	s_addc_u32 s81, s29, 0
	s_add_u32 s34, s28, 2
	s_addc_u32 s35, s29, 0
	s_lshl_b64 s[52:53], s[34:35], s61
	s_add_u32 s29, s2, s52
	s_addc_u32 s52, s3, s53
	s_cmp_eq_u32 s65, s28
	s_cselect_b32 s53, s9, s52
	s_cselect_b32 s52, s8, s29
	s_cselect_b32 s82, s50, s73
	s_cselect_b32 s83, s51, s75
	s_add_u32 s28, s52, s40
	s_addc_u32 s29, s53, s41
	s_add_i32 s84, 0, 0x10000
	s_add_i32 s85, 0, 0x14000
	v_add_u32_e32 v140, s84, v225
	v_add_u32_e32 v156, s85, v225
	ds_read_b128 v[124:127], v140
	ds_read_b128 v[128:131], v140 offset:1024
	ds_read_b128 v[136:139], v140 offset:2048
	ds_read_b128 v[140:143], v140 offset:3072
	ds_read_b128 v[144:147], v156
	ds_read_b128 v[148:151], v156 offset:1024
	ds_read_b128 v[152:155], v156 offset:2048
	ds_read_b128 v[156:159], v156 offset:3072
	s_lshl_b64 s[80:81], s[80:81], s61
	s_add_u32 s80, s71, s80
	s_addc_u32 s81, s72, s81
	v_lshl_add_u64 v[178:179], s[80:81], 0, v[194:195]
	s_add_i32 m0, s23, 0xc000
	ds_read_b128 v[160:163], v226
	ds_read_b128 v[164:167], v226 offset:1024
	ds_read_b128 v[168:171], v226 offset:2048
	ds_read_b128 v[172:175], v226 offset:3072
	ds_read_b128 v[202:205], v226 offset:4096
	ds_read_b128 v[206:209], v226 offset:5120
	ds_read_b128 v[210:213], v226 offset:6144
	ds_read_b128 v[214:217], v226 offset:7168
	global_load_lds_dwordx4 v[178:179], off
	v_lshl_add_u64 v[178:179], s[80:81], 0, v[198:199]
	s_add_i32 m0, s23, 0xe000
	s_nop 0
	global_load_lds_dwordx4 v[178:179], off
	s_waitcnt vmcnt(8)
	s_waitcnt lgkmcnt(0)
	s_barrier
	v_mfma_f32_16x16x32_bf16 v[132:135], v[124:127], v[160:163], v[132:135]
	v_mfma_f32_16x16x32_bf16 v[120:123], v[136:139], v[160:163], v[120:123]
	v_mfma_f32_16x16x32_bf16 v[108:111], v[124:127], v[168:171], v[108:111]
	v_mfma_f32_16x16x32_bf16 v[104:107], v[136:139], v[168:171], v[104:107]
	v_mfma_f32_16x16x32_bf16 v[92:95], v[124:127], v[202:205], v[92:95]
	v_mfma_f32_16x16x32_bf16 v[88:91], v[136:139], v[202:205], v[88:91]
	v_mfma_f32_16x16x32_bf16 v[76:79], v[124:127], v[210:213], v[76:79]
	v_mfma_f32_16x16x32_bf16 v[72:75], v[136:139], v[210:213], v[72:75]
	v_mfma_f32_16x16x32_bf16 v[132:135], v[128:131], v[164:167], v[132:135]
	v_mfma_f32_16x16x32_bf16 v[120:123], v[140:143], v[164:167], v[120:123]
	v_mfma_f32_16x16x32_bf16 v[108:111], v[128:131], v[172:175], v[108:111]
	v_mfma_f32_16x16x32_bf16 v[104:107], v[140:143], v[172:175], v[104:107]
	v_mfma_f32_16x16x32_bf16 v[92:95], v[128:131], v[206:209], v[92:95]
	v_mfma_f32_16x16x32_bf16 v[88:91], v[140:143], v[206:209], v[88:91]
	v_mfma_f32_16x16x32_bf16 v[76:79], v[128:131], v[214:217], v[76:79]
	v_mfma_f32_16x16x32_bf16 v[72:75], v[140:143], v[214:217], v[72:75]
	v_mfma_f32_16x16x32_bf16 v[116:119], v[144:147], v[160:163], v[116:119]
	v_mfma_f32_16x16x32_bf16 v[112:115], v[152:155], v[160:163], v[112:115]
	v_mfma_f32_16x16x32_bf16 v[100:103], v[144:147], v[168:171], v[100:103]
	v_mfma_f32_16x16x32_bf16 v[96:99], v[152:155], v[168:171], v[96:99]
	v_mfma_f32_16x16x32_bf16 v[84:87], v[144:147], v[202:205], v[84:87]
	v_mfma_f32_16x16x32_bf16 v[80:83], v[152:155], v[202:205], v[80:83]
	v_mfma_f32_16x16x32_bf16 v[68:71], v[144:147], v[210:213], v[68:71]
	v_mfma_f32_16x16x32_bf16 v[64:67], v[152:155], v[210:213], v[64:67]
	v_mfma_f32_16x16x32_bf16 v[116:119], v[148:151], v[164:167], v[116:119]
	v_mfma_f32_16x16x32_bf16 v[112:115], v[156:159], v[164:167], v[112:115]
	v_mfma_f32_16x16x32_bf16 v[100:103], v[148:151], v[172:175], v[100:103]
	v_mfma_f32_16x16x32_bf16 v[96:99], v[156:159], v[172:175], v[96:99]
	v_mfma_f32_16x16x32_bf16 v[84:87], v[148:151], v[206:209], v[84:87]
	v_mfma_f32_16x16x32_bf16 v[80:83], v[156:159], v[206:209], v[80:83]
	v_mfma_f32_16x16x32_bf16 v[68:71], v[148:151], v[214:217], v[68:71]
	v_mfma_f32_16x16x32_bf16 v[64:67], v[156:159], v[214:217], v[64:67]
	s_barrier
; #define PG8_STAGE(bufoff, gbase, voff) do { _Pragma("unroll") for (int _i = 0; _i < 2; ++_i) \
;         __builtin_amdgcn_global_load_lds((const unsigned*)((const char*)(gbase) + (voff)[_i]), (LAS unsigned*)(lds + (bufoff) + ldsw + _i * 8192), 16, 0, 0); } while (0)
; #define PG8_LDA(dst, b, h) do { _Pragma("unroll") for (int m = 0; m < 4; ++m) _Pragma("unroll") for (int k = 0; k < 2; ++k) dst[m][k] = *(const LAS bf16x8*)(lds + PG8_SA(b, h) + aoff + m * 2048 + k * 1024); } while (0)
; #define PG8_LDB(dst, b, h) do { _Pragma("unroll") for (int n = 0; n < 2; ++n) _Pragma("unroll") for (int k = 0; k < 2; ++k) dst[n][k] = *(const LAS bf16x8*)(lds + PG8_SB(b, h) + boff + n * 2048 + k * 1024); } while (0)
; #define PG8_MMA(ai, bj, At, Bt) do { __builtin_amdgcn_s_setprio(1); _Pragma("unroll") for (int m = 0; m < 4; ++m) _Pragma("unroll") for (int n = 0; n < 2; ++n) _Pragma("unroll") for (int k = 0; k < 2; ++k) \
;         acc[ai][bj][m][n] = __builtin_amdgcn_mfma_f32_16x16x32_bf16(Bt[n][k], At[m][k], acc[ai][bj][m][n], 0, 0, 0); __builtin_amdgcn_s_setprio(0); } while (0)
; #define PG8_WAIT_V(n) asm volatile("s_waitcnt vmcnt(" #n ")" ::: "memory")
; #define PG8_WAIT_L(n) asm volatile("s_waitcnt lgkmcnt(" #n ")" ::: "memory")
; #define PG8_BAR __builtin_amdgcn_s_barrier()
; #define PG8_SCHED __builtin_amdgcn_sched_barrier(0)
; template <class Epi>
; __device__ __forceinline__ void gemm_phase(LAS unsigned char* lds, const Gemm g, const StaticOrder& S, const Epi& E, const int tid) {
;     ...
;             PG8_LDA(At, 0, 1); PG8_STAGE(PG8_SB(0, 0), b2, voffB); PG8_STAGE(PG8_SB(0, 1), b2 + hstepB, voffB); PG8_STAGE(PG8_SA(0, 0), a2, voffA);
;             PG8_WAIT_V(8); PG8_WAIT_L(0); PG8_BAR; PG8_MMA(1, 0, At, B0); PG8_MMA(1, 1, At, B1); PG8_BAR; PG8_SCHED;
;             PG8_LDB(B0, 1, 0); PG8_LDB(B1, 1, 1); PG8_SCHED; PG8_LDA(At, 1, 0); PG8_STAGE(PG8_SA(0, 1), a2 + hstepA, voffA);
;             PG8_WAIT_V(8); PG8_WAIT_L(0); PG8_BAR; PG8_MMA(0, 0, At, B0); PG8_MMA(0, 1, At, B1); PG8_BAR; PG8_SCHED;
	s_add_i32 s80, s84, s17
	v_lshl_add_u64 v[178:179], s[82:83], 0, v[176:177]
	s_mov_b32 m0, s80
	ds_read_b128 v[160:163], v226 offset:16384
	ds_read_b128 v[164:167], v226 offset:17408
	ds_read_b128 v[168:171], v226 offset:18432
	ds_read_b128 v[172:175], v226 offset:19456
	ds_read_b128 v[202:205], v226 offset:20480
	ds_read_b128 v[206:209], v226 offset:21504
	ds_read_b128 v[210:213], v226 offset:22528
	ds_read_b128 v[214:217], v226 offset:23552
	global_load_lds_dwordx4 v[178:179], off
	s_add_i32 m0, s80, 0x2000
	s_add_u32 s80, s82, s42
	v_lshl_add_u64 v[180:181], s[82:83], 0, v[196:197]
	s_addc_u32 s81, s83, s43
	s_add_i32 s82, s85, s17
	global_load_lds_dwordx4 v[180:181], off
	v_lshl_add_u64 v[218:219], s[80:81], 0, v[176:177]
	s_mov_b32 m0, s82
	v_lshl_add_u64 v[228:229], s[80:81], 0, v[196:197]
	global_load_lds_dwordx4 v[218:219], off
	s_add_i32 m0, s82, 0x2000
	v_lshl_add_u64 v[230:231], s[52:53], 0, v[194:195]
	global_load_lds_dwordx4 v[228:229], off
	s_mov_b32 m0, s23
	s_nop 0
	global_load_lds_dwordx4 v[230:231], off
	v_lshl_add_u64 v[230:231], s[52:53], 0, v[198:199]
	s_mov_b32 m0, s54
	s_nop 0
	global_load_lds_dwordx4 v[230:231], off
	s_waitcnt vmcnt(8)
	s_waitcnt lgkmcnt(0)
	s_barrier
	v_mfma_f32_16x16x32_bf16 v[60:63], v[124:127], v[160:163], v[60:63]
	v_mfma_f32_16x16x32_bf16 v[56:59], v[136:139], v[160:163], v[56:59]
	v_mfma_f32_16x16x32_bf16 v[44:47], v[124:127], v[168:171], v[44:47]
	v_mfma_f32_16x16x32_bf16 v[40:43], v[136:139], v[168:171], v[40:43]
	v_mfma_f32_16x16x32_bf16 v[28:31], v[124:127], v[202:205], v[28:31]
	v_mfma_f32_16x16x32_bf16 v[24:27], v[136:139], v[202:205], v[24:27]
	v_mfma_f32_16x16x32_bf16 v[12:15], v[124:127], v[210:213], v[12:15]
	v_mfma_f32_16x16x32_bf16 v[8:11], v[136:139], v[210:213], v[8:11]
	v_mfma_f32_16x16x32_bf16 v[60:63], v[128:131], v[164:167], v[60:63]
	v_mfma_f32_16x16x32_bf16 v[56:59], v[140:143], v[164:167], v[56:59]
	v_mfma_f32_16x16x32_bf16 v[44:47], v[128:131], v[172:175], v[44:47]
	v_mfma_f32_16x16x32_bf16 v[40:43], v[140:143], v[172:175], v[40:43]
	v_mfma_f32_16x16x32_bf16 v[28:31], v[128:131], v[206:209], v[28:31]
	v_mfma_f32_16x16x32_bf16 v[24:27], v[140:143], v[206:209], v[24:27]
	v_mfma_f32_16x16x32_bf16 v[12:15], v[128:131], v[214:217], v[12:15]
	v_mfma_f32_16x16x32_bf16 v[8:11], v[140:143], v[214:217], v[8:11]
	v_mfma_f32_16x16x32_bf16 v[52:55], v[144:147], v[160:163], v[52:55]
	v_mfma_f32_16x16x32_bf16 v[48:51], v[152:155], v[160:163], v[48:51]
	v_mfma_f32_16x16x32_bf16 v[36:39], v[144:147], v[168:171], v[36:39]
	v_mfma_f32_16x16x32_bf16 v[32:35], v[152:155], v[168:171], v[32:35]
	v_mfma_f32_16x16x32_bf16 v[20:23], v[144:147], v[202:205], v[20:23]
	v_mfma_f32_16x16x32_bf16 v[16:19], v[152:155], v[202:205], v[16:19]
	v_mfma_f32_16x16x32_bf16 v[4:7], v[144:147], v[210:213], v[4:7]
	v_mfma_f32_16x16x32_bf16 v[0:3], v[152:155], v[210:213], v[0:3]
	v_mfma_f32_16x16x32_bf16 v[52:55], v[148:151], v[164:167], v[52:55]
	v_mfma_f32_16x16x32_bf16 v[48:51], v[156:159], v[164:167], v[48:51]
	v_mfma_f32_16x16x32_bf16 v[36:39], v[148:151], v[172:175], v[36:39]
	v_mfma_f32_16x16x32_bf16 v[32:35], v[156:159], v[172:175], v[32:35]
	v_mfma_f32_16x16x32_bf16 v[20:23], v[148:151], v[206:209], v[20:23]
	v_mfma_f32_16x16x32_bf16 v[16:19], v[156:159], v[206:209], v[16:19]
	v_mfma_f32_16x16x32_bf16 v[4:7], v[148:151], v[214:217], v[4:7]
	v_mfma_f32_16x16x32_bf16 v[0:3], v[156:159], v[214:217], v[0:3]
	s_barrier
	s_add_i32 s80, 0, 0x18000
	s_add_i32 s81, 0, 0x1c000
	v_add_u32_e32 v140, s80, v225
	v_add_u32_e32 v156, s81, v225
	ds_read_b128 v[124:127], v140
	ds_read_b128 v[128:131], v140 offset:1024
	ds_read_b128 v[136:139], v140 offset:2048
	ds_read_b128 v[140:143], v140 offset:3072
	ds_read_b128 v[144:147], v156
	ds_read_b128 v[148:151], v156 offset:1024
	ds_read_b128 v[152:155], v156 offset:2048
	ds_read_b128 v[156:159], v156 offset:3072
	s_add_u32 s52, s52, s21
	s_addc_u32 s53, s53, 0
	s_mov_b32 m0, s55
	v_lshl_add_u64 v[230:231], s[52:53], 0, v[194:195]
	ds_read_b128 v[160:163], v226 offset:32768
	ds_read_b128 v[164:167], v226 offset:33792
	ds_read_b128 v[168:171], v226 offset:34816
	ds_read_b128 v[172:175], v226 offset:35840
	ds_read_b128 v[202:205], v226 offset:36864
	ds_read_b128 v[206:209], v226 offset:37888
	ds_read_b128 v[210:213], v226 offset:38912
	ds_read_b128 v[214:217], v226 offset:39936
	global_load_lds_dwordx4 v[230:231], off
	v_lshl_add_u64 v[230:231], s[52:53], 0, v[198:199]
	s_mov_b32 m0, s56
	s_nop 0
	global_load_lds_dwordx4 v[230:231], off
	s_waitcnt vmcnt(8)
	s_waitcnt lgkmcnt(0)
	s_barrier
; #define PG8_STAGE(bufoff, gbase, voff) do { _Pragma("unroll") for (int _i = 0; _i < 2; ++_i) \
;         __builtin_amdgcn_global_load_lds((const unsigned*)((const char*)(gbase) + (voff)[_i]), (LAS unsigned*)(lds + (bufoff) + ldsw + _i * 8192), 16, 0, 0); } while (0)
; #define PG8_LDA(dst, b, h) do { _Pragma("unroll") for (int m = 0; m < 4; ++m) _Pragma("unroll") for (int k = 0; k < 2; ++k) dst[m][k] = *(const LAS bf16x8*)(lds + PG8_SA(b, h) + aoff + m * 2048 + k * 1024); } while (0)
; #define PG8_MMA(ai, bj, At, Bt) do { __builtin_amdgcn_s_setprio(1); _Pragma("unroll") for (int m = 0; m < 4; ++m) _Pragma("unroll") for (int n = 0; n < 2; ++n) _Pragma("unroll") for (int k = 0; k < 2; ++k) \
;         acc[ai][bj][m][n] = __builtin_amdgcn_mfma_f32_16x16x32_bf16(Bt[n][k], At[m][k], acc[ai][bj][m][n], 0, 0, 0); __builtin_amdgcn_s_setprio(0); } while (0)
; #define PG8_WAIT_V(n) asm volatile("s_waitcnt vmcnt(" #n ")" ::: "memory")
; #define PG8_WAIT_L(n) asm volatile("s_waitcnt lgkmcnt(" #n ")" ::: "memory")
; #define PG8_BAR __builtin_amdgcn_s_barrier()
; #define PG8_SCHED __builtin_amdgcn_sched_barrier(0)
; template <class Epi>
; __device__ __forceinline__ void gemm_phase(LAS unsigned char* lds, const Gemm g, const StaticOrder& S, const Epi& E, const int tid) {
;     ...
;             PG8_WAIT_V(8); PG8_WAIT_L(0); PG8_BAR; PG8_MMA(0, 0, At, B0); PG8_MMA(0, 1, At, B1); PG8_BAR; PG8_SCHED;
;             PG8_LDA(At, 1, 1); PG8_STAGE(PG8_SB(1, 0), b3, voffB); PG8_STAGE(PG8_SB(1, 1), b3 + hstepB, voffB); PG8_STAGE(PG8_SA(1, 0), a3, voffA);
;             PG8_WAIT_V(8); PG8_WAIT_L(0); PG8_BAR; PG8_MMA(1, 0, At, B0); PG8_MMA(1, 1, At, B1); PG8_BAR; PG8_SCHED;
;         }
	v_mfma_f32_16x16x32_bf16 v[132:135], v[124:127], v[160:163], v[132:135]
	v_mfma_f32_16x16x32_bf16 v[120:123], v[136:139], v[160:163], v[120:123]
	v_mfma_f32_16x16x32_bf16 v[108:111], v[124:127], v[168:171], v[108:111]
	v_mfma_f32_16x16x32_bf16 v[104:107], v[136:139], v[168:171], v[104:107]
	v_mfma_f32_16x16x32_bf16 v[92:95], v[124:127], v[202:205], v[92:95]
	v_mfma_f32_16x16x32_bf16 v[88:91], v[136:139], v[202:205], v[88:91]
	v_mfma_f32_16x16x32_bf16 v[76:79], v[124:127], v[210:213], v[76:79]
	v_mfma_f32_16x16x32_bf16 v[72:75], v[136:139], v[210:213], v[72:75]
	v_mfma_f32_16x16x32_bf16 v[132:135], v[128:131], v[164:167], v[132:135]
	v_mfma_f32_16x16x32_bf16 v[120:123], v[140:143], v[164:167], v[120:123]
	v_mfma_f32_16x16x32_bf16 v[108:111], v[128:131], v[172:175], v[108:111]
	v_mfma_f32_16x16x32_bf16 v[104:107], v[140:143], v[172:175], v[104:107]
	v_mfma_f32_16x16x32_bf16 v[92:95], v[128:131], v[206:209], v[92:95]
	v_mfma_f32_16x16x32_bf16 v[88:91], v[140:143], v[206:209], v[88:91]
	v_mfma_f32_16x16x32_bf16 v[76:79], v[128:131], v[214:217], v[76:79]
	v_mfma_f32_16x16x32_bf16 v[72:75], v[140:143], v[214:217], v[72:75]
	v_mfma_f32_16x16x32_bf16 v[116:119], v[144:147], v[160:163], v[116:119]
	v_mfma_f32_16x16x32_bf16 v[112:115], v[152:155], v[160:163], v[112:115]
	v_mfma_f32_16x16x32_bf16 v[100:103], v[144:147], v[168:171], v[100:103]
	v_mfma_f32_16x16x32_bf16 v[96:99], v[152:155], v[168:171], v[96:99]
	v_mfma_f32_16x16x32_bf16 v[84:87], v[144:147], v[202:205], v[84:87]
	v_mfma_f32_16x16x32_bf16 v[80:83], v[152:155], v[202:205], v[80:83]
	v_mfma_f32_16x16x32_bf16 v[68:71], v[144:147], v[210:213], v[68:71]
	v_mfma_f32_16x16x32_bf16 v[64:67], v[152:155], v[210:213], v[64:67]
	v_mfma_f32_16x16x32_bf16 v[116:119], v[148:151], v[164:167], v[116:119]
	v_mfma_f32_16x16x32_bf16 v[112:115], v[156:159], v[164:167], v[112:115]
	v_mfma_f32_16x16x32_bf16 v[100:103], v[148:151], v[172:175], v[100:103]
	v_mfma_f32_16x16x32_bf16 v[96:99], v[156:159], v[172:175], v[96:99]
	v_mfma_f32_16x16x32_bf16 v[84:87], v[148:151], v[206:209], v[84:87]
	v_mfma_f32_16x16x32_bf16 v[80:83], v[156:159], v[206:209], v[80:83]
	v_mfma_f32_16x16x32_bf16 v[68:71], v[148:151], v[214:217], v[68:71]
	v_mfma_f32_16x16x32_bf16 v[64:67], v[156:159], v[214:217], v[64:67]
	s_barrier
	s_add_i32 s52, s80, s17
	v_lshl_add_u64 v[178:179], v[178:179], 0, s[36:37]
	s_mov_b32 m0, s52
	ds_read_b128 v[160:163], v226 offset:49152
	ds_read_b128 v[164:167], v226 offset:50176
	ds_read_b128 v[168:171], v226 offset:51200
	ds_read_b128 v[172:175], v226 offset:52224
	ds_read_b128 v[202:205], v226 offset:53248
	ds_read_b128 v[206:209], v226 offset:54272
	ds_read_b128 v[210:213], v226 offset:55296
	ds_read_b128 v[214:217], v226 offset:56320
	global_load_lds_dwordx4 v[178:179], off
	v_lshl_add_u64 v[178:179], v[180:181], 0, s[36:37]
	s_add_i32 m0, s52, 0x2000
	s_add_i32 s52, s81, s17
	global_load_lds_dwordx4 v[178:179], off
	v_lshl_add_u64 v[178:179], v[218:219], 0, s[36:37]
	s_mov_b32 m0, s52
	s_nop 0
	global_load_lds_dwordx4 v[178:179], off
	v_lshl_add_u64 v[178:179], v[228:229], 0, s[36:37]
	s_add_i32 m0, s52, 0x2000
	s_nop 0
	global_load_lds_dwordx4 v[178:179], off
	v_lshl_add_u64 v[178:179], s[28:29], 0, v[194:195]
	s_mov_b32 m0, s59
	s_nop 0
	global_load_lds_dwordx4 v[178:179], off
	v_lshl_add_u64 v[178:179], s[28:29], 0, v[198:199]
	s_mov_b32 m0, s60
	s_nop 0
	global_load_lds_dwordx4 v[178:179], off
	s_waitcnt vmcnt(8)
	s_waitcnt lgkmcnt(0)
	s_barrier
	v_mfma_f32_16x16x32_bf16 v[60:63], v[124:127], v[160:163], v[60:63]
	v_mfma_f32_16x16x32_bf16 v[56:59], v[136:139], v[160:163], v[56:59]
	v_mfma_f32_16x16x32_bf16 v[44:47], v[124:127], v[168:171], v[44:47]
	v_mfma_f32_16x16x32_bf16 v[40:43], v[136:139], v[168:171], v[40:43]
	v_mfma_f32_16x16x32_bf16 v[28:31], v[124:127], v[202:205], v[28:31]
	v_mfma_f32_16x16x32_bf16 v[24:27], v[136:139], v[202:205], v[24:27]
	v_mfma_f32_16x16x32_bf16 v[12:15], v[124:127], v[210:213], v[12:15]
	v_mfma_f32_16x16x32_bf16 v[8:11], v[136:139], v[210:213], v[8:11]
	v_mfma_f32_16x16x32_bf16 v[60:63], v[128:131], v[164:167], v[60:63]
	v_mfma_f32_16x16x32_bf16 v[56:59], v[140:143], v[164:167], v[56:59]
	v_mfma_f32_16x16x32_bf16 v[44:47], v[128:131], v[172:175], v[44:47]
	v_mfma_f32_16x16x32_bf16 v[40:43], v[140:143], v[172:175], v[40:43]
	v_mfma_f32_16x16x32_bf16 v[28:31], v[128:131], v[206:209], v[28:31]
	v_mfma_f32_16x16x32_bf16 v[24:27], v[140:143], v[206:209], v[24:27]
	v_mfma_f32_16x16x32_bf16 v[12:15], v[128:131], v[214:217], v[12:15]
	v_mfma_f32_16x16x32_bf16 v[8:11], v[140:143], v[214:217], v[8:11]
	v_mfma_f32_16x16x32_bf16 v[52:55], v[144:147], v[160:163], v[52:55]
	v_mfma_f32_16x16x32_bf16 v[48:51], v[152:155], v[160:163], v[48:51]
	v_mfma_f32_16x16x32_bf16 v[36:39], v[144:147], v[168:171], v[36:39]
	v_mfma_f32_16x16x32_bf16 v[32:35], v[152:155], v[168:171], v[32:35]
	v_mfma_f32_16x16x32_bf16 v[20:23], v[144:147], v[202:205], v[20:23]
	v_mfma_f32_16x16x32_bf16 v[16:19], v[152:155], v[202:205], v[16:19]
	v_mfma_f32_16x16x32_bf16 v[4:7], v[144:147], v[210:213], v[4:7]
	v_mfma_f32_16x16x32_bf16 v[0:3], v[152:155], v[210:213], v[0:3]
	v_mfma_f32_16x16x32_bf16 v[52:55], v[148:151], v[164:167], v[52:55]
	v_mfma_f32_16x16x32_bf16 v[48:51], v[156:159], v[164:167], v[48:51]
	v_mfma_f32_16x16x32_bf16 v[36:39], v[148:151], v[172:175], v[36:39]
	v_mfma_f32_16x16x32_bf16 v[32:35], v[156:159], v[172:175], v[32:35]
	v_mfma_f32_16x16x32_bf16 v[20:23], v[148:151], v[206:209], v[20:23]
	v_mfma_f32_16x16x32_bf16 v[16:19], v[156:159], v[206:209], v[16:19]
	v_mfma_f32_16x16x32_bf16 v[4:7], v[148:151], v[214:217], v[4:7]
	v_mfma_f32_16x16x32_bf16 v[0:3], v[156:159], v[214:217], v[0:3]
	s_barrier
	s_add_u32 s73, s73, 0x100
	s_addc_u32 s75, s75, 0
	s_cmp_ge_u32 s34, s58
	s_mov_b64 s[28:29], s[34:35]
	s_cbranch_scc0 .LBB0_393
; __device__ __forceinline__ f32x4 gload16_nt(const void* p) { f32x4 v; asm volatile("global_load_dwordx4 %0, %1, off nt" : "=v"(v) : "v"(p) : "memory"); return v; }
; #define WAIT16(a) asm volatile("s_waitcnt vmcnt(0)" : "+v"(a[0]), "+v"(a[1]), "+v"(a[2]), "+v"(a[3]), "+v"(a[4]), "+v"(a[5]), "+v"(a[6]), "+v"(a[7]), "+v"(a[8]), "+v"(a[9]), "+v"(a[10]), "+v"(a[11]), "+v"(a[12]), "+v"(a[13]), "+v"(a[14]), "+v"(a[15]) :: "memory")
; #define PG8_BAR __builtin_amdgcn_s_barrier()
;     __device__ __forceinline__ void operator()(const AccT& acc, const Unit& u, int wr, int wc, int fr, int fq, LAS unsigned char* stg) const {
;         const int row0 = u.pm * BM + wr * 64 + fr, col0 = u.pn * BM + wc * 64 + 8 * fq;
;         const size_t blk0 = ((size_t)(u.pm * 16 + wr * 4) * 32 + (u.pn * 8 + wc * 2)) * 512 + fr * 32 + 8 * fq;
;         constexpr bool last = LAST;
; #pragma unroll
;         for (int ai = 0; ai < 2; ++ai) {
;             f32x4 pre[16];
; #pragma unroll
;             for (int m = 0; m < 4; ++m) {
;                 const size_t boff = blk0 + (size_t)(ai * 8 + m) * (32 * 512);
;                 pre[m * 4 + 0] = gload16_nt(XB + boff); pre[m * 4 + 1] = gload16_nt(XB + boff + 512); pre[m * 4 + 2] = gload16_nt(XL + boff); pre[m * 4 + 3] = gload16_nt(XL + boff + 512);
;             }
;             WAIT16(pre);
; template <class Epi>
; __device__ __forceinline__ void gemm_phase(LAS unsigned char* lds, const Gemm g, const StaticOrder& S, const Epi& E, const int tid) {
;     ...
;         if (wr == 0) PG8_BAR;
.LBB0_396:
	s_lshl_b32 s2, s70, 4
	s_lshl_b32 s28, s30, 3
	s_add_i32 s2, s2, s63
	s_or_b32 s28, s28, s64
	s_ashr_i32 s3, s2, 31
	s_ashr_i32 s29, s28, 31
	s_lshl_b64 s[2:3], s[2:3], 14
	s_lshl_b64 s[28:29], s[28:29], 9
	s_add_u32 s2, s2, s28
	s_addc_u32 s3, s3, s29
	v_mov_b32_e32 v125, s3
	v_or_b32_e32 v124, s2, v200
	v_lshlrev_b64 v[204:205], 1, v[124:125]
	v_lshl_add_u64 v[178:179], s[24:25], 0, v[204:205]
	global_load_dwordx4 v[230:233], v[178:179], off nt
	v_lshl_add_u64 v[124:125], v[178:179], 0, s[38:39]
	global_load_dwordx4 v[234:237], v[124:125], off nt
	v_lshl_add_u64 v[218:219], s[18:19], 0, v[204:205]
	global_load_dwordx4 v[238:241], v[218:219], off nt
	v_lshl_add_u64 v[124:125], v[218:219], 0, s[38:39]
	s_mov_b64 s[2:3], 0x8000
	global_load_dwordx4 v[242:245], v[124:125], off nt
	v_lshl_add_u64 v[124:125], v[204:205], 0, s[2:3]
	v_lshl_add_u64 v[216:217], s[24:25], 0, v[124:125]
	global_load_dwordx4 v[168:171], v[216:217], off nt
	v_lshl_add_u64 v[126:127], v[216:217], 0, s[38:39]
	global_load_dwordx4 v[160:163], v[126:127], off nt
	v_lshl_add_u64 v[214:215], s[18:19], 0, v[124:125]
	global_load_dwordx4 v[172:175], v[214:215], off nt
	v_lshl_add_u64 v[124:125], v[214:215], 0, s[38:39]
	s_mov_b64 s[2:3], 0x10000
	global_load_dwordx4 v[164:167], v[124:125], off nt
	v_lshl_add_u64 v[124:125], v[204:205], 0, s[2:3]
	v_lshl_add_u64 v[212:213], s[24:25], 0, v[124:125]
	global_load_dwordx4 v[152:155], v[212:213], off nt
	v_lshl_add_u64 v[126:127], v[212:213], 0, s[38:39]
	global_load_dwordx4 v[144:147], v[126:127], off nt
	s_mov_b64 s[2:3], 0x18000
	v_lshl_add_u64 v[210:211], s[18:19], 0, v[124:125]
	global_load_dwordx4 v[156:159], v[210:211], off nt
	v_lshl_add_u64 v[128:129], v[204:205], 0, s[2:3]
	v_and_b32_e32 v181, 64, v223
	v_lshl_add_u64 v[124:125], v[210:211], 0, s[38:39]
	global_load_dwordx4 v[148:151], v[124:125], off nt
	v_lshl_add_u64 v[208:209], s[24:25], 0, v[128:129]
	v_xor_b32_e32 v180, 16, v223
	v_add_u32_e32 v181, 64, v181
	global_load_dwordx4 v[136:139], v[208:209], off nt
	v_lshl_add_u64 v[124:125], v[208:209], 0, s[38:39]
	v_cmp_lt_i32_e32 vcc, v180, v181
	global_load_dwordx4 v[124:127], v[124:125], off nt
	v_lshl_add_u64 v[206:207], s[18:19], 0, v[128:129]
	global_load_dwordx4 v[140:143], v[206:207], off nt
	v_lshl_add_u64 v[128:129], v[206:207], 0, s[38:39]
	v_cndmask_b32_e32 v180, v223, v180, vcc
	v_lshlrev_b32_e32 v228, 2, v180
	v_xor_b32_e32 v180, 32, v223
	global_load_dwordx4 v[128:131], v[128:129], off nt
	v_cmp_lt_i32_e32 vcc, v180, v181
	s_and_b64 s[100:101], exec, s[48:49]
	s_cbranch_scc0 .Lalign_skip_res
	s_barrier
; __device__ __forceinline__ unsigned cvtpk(float lo, float hi) { f32x2_t v = {lo, hi}; bf16x2_t b = __builtin_convertvector(v, bf16x2_t); return __builtin_bit_cast(unsigned, b); }
;     __device__ __forceinline__ void operator()(const AccT& acc, const Unit& u, int wr, int wc, int fr, int fq, LAS unsigned char* stg) const {
;     ...
; #pragma unroll
;             for (int m = 0; m < 4; ++m) {
;                 const size_t boff = blk0 + (size_t)(ai * 8 + m) * (32 * 512);
;                 const size_t off = (size_t)(row0 + ai * HALF + m * 16) * D + col0;
;                 float ssq = 0.f;
; #pragma unroll
;                 for (int bj = 0; bj < 2; ++bj) {
;                     const u32x4 hi = __builtin_bit_cast(u32x4, pre[m * 4 + bj]), lo = __builtin_bit_cast(u32x4, pre[m * 4 + 2 + bj]);
;                     f32x4 o0, o1;
;                     o0.x = bf_lo(hi.x) + bf_lo(lo.x); o0.y = bf_hi(hi.x) + bf_hi(lo.x); o0.z = bf_lo(hi.y) + bf_lo(lo.y); o0.w = bf_hi(hi.y) + bf_hi(lo.y);
;                     o1.x = bf_lo(hi.z) + bf_lo(lo.z); o1.y = bf_hi(hi.z) + bf_hi(lo.z); o1.z = bf_lo(hi.w) + bf_lo(lo.w); o1.w = bf_hi(hi.w) + bf_hi(lo.w);
;                     o0 += acc[ai][bj][m][0]; o1 += acc[ai][bj][m][1];
;                     if constexpr (last) { *(f32x4*)(fout + off + bj * 32) = o0; *(f32x4*)(fout + off + bj * 32 + 4) = o1; }
;                     else {
;                         ssq += (o0.x * o0.x + o0.y * o0.y) + (o0.z * o0.z + o0.w * o0.w) + (o1.x * o1.x + o1.y * o1.y) + (o1.z * o1.z + o1.w * o1.w);
;                         u32x4 w; w.x = cvtpk(o0.x, o0.y); w.y = cvtpk(o0.z, o0.w); w.z = cvtpk(o1.x, o1.y); w.w = cvtpk(o1.z, o1.w);
;                         *(u32x4*)(XB + boff + bj * 512) = w;
;                         u32x4 l;
;                         l.x = cvtpk(o0.x - bf_lo(w.x), o0.y - bf_hi(w.x)); l.y = cvtpk(o0.z - bf_lo(w.y), o0.w - bf_hi(w.y));
;                         l.z = cvtpk(o1.x - bf_lo(w.z), o1.y - bf_hi(w.z)); l.w = cvtpk(o1.z - bf_lo(w.w), o1.w - bf_hi(w.w));
;                         __builtin_nontemporal_store(l, (u32x4*)(XL + boff + bj * 512));
;                     }
;                 }
;                 if constexpr (!last) {
;                     ssq += __shfl_xor(ssq, 16); ssq += __shfl_xor(ssq, 32);
;                     if (fq == 0) SS[(size_t)(row0 + ai * HALF + m * 16) * 16 + u.pn * 4 + wc] = ssq;
.Lalign_skip_res:
	s_waitcnt vmcnt(0)
	v_lshl_add_u32 v202, s70, 8, v193
	v_and_b32_e32 v181, 0xffff0000, v230
	v_cndmask_b32_e32 v180, v223, v180, vcc
	v_lshlrev_b32_e32 v227, 2, v180
	v_lshlrev_b32_e32 v180, 16, v230
	v_lshlrev_b32_e32 v246, 16, v238
	v_and_b32_e32 v247, 0xffff0000, v238
	v_lshlrev_b32_e32 v230, 16, v231
	v_and_b32_e32 v231, 0xffff0000, v231
	v_lshlrev_b32_e32 v238, 16, v239
	v_and_b32_e32 v239, 0xffff0000, v239
	v_pk_add_f32 v[180:181], v[180:181], v[246:247]
	v_pk_add_f32 v[230:231], v[230:231], v[238:239]
	v_lshlrev_b32_e32 v238, 16, v232
	v_and_b32_e32 v239, 0xffff0000, v232
	v_lshlrev_b32_e32 v246, 16, v240
	v_and_b32_e32 v247, 0xffff0000, v240
	v_pk_add_f32 v[238:239], v[238:239], v[246:247]
	v_pk_add_f32 v[134:135], v[134:135], v[230:231]
	v_pk_add_f32 v[132:133], v[132:133], v[180:181]
	v_pk_add_f32 v[230:231], v[120:121], v[238:239]
	v_mul_f32_e32 v120, v133, v133
	v_mul_f32_e32 v121, v135, v135
	v_lshlrev_b32_e32 v232, 16, v233
	v_and_b32_e32 v233, 0xffff0000, v233
	v_lshlrev_b32_e32 v240, 16, v241
	v_and_b32_e32 v241, 0xffff0000, v241
	v_fmac_f32_e32 v120, v132, v132
	v_fmac_f32_e32 v121, v134, v134
	v_pk_add_f32 v[232:233], v[232:233], v[240:241]
	v_add_f32_e32 v120, v120, v121
	v_mul_f32_e32 v121, v231, v231
	v_pk_add_f32 v[180:181], v[122:123], v[232:233]
	v_fmac_f32_e32 v121, v230, v230
	v_add_f32_e32 v120, v121, v120
	v_mul_f32_e32 v121, v181, v181
	v_fmac_f32_e32 v121, v180, v180
	v_add_f32_e32 v203, v121, v120
	v_cvt_pk_bf16_f32 v120, v132, v133
	v_lshlrev_b32_e32 v232, 16, v120
	v_and_b32_e32 v233, 0xffff0000, v120
	v_cvt_pk_bf16_f32 v121, v134, v135
	v_cvt_pk_bf16_f32 v122, v230, v231
	v_cvt_pk_bf16_f32 v123, v180, v181
	v_pk_add_f32 v[132:133], v[132:133], v[232:233] neg_lo:[0,1] neg_hi:[0,1]
	global_store_dwordx4 v[178:179], v[120:123], off
	s_lshl_b32 s28, s30, 2
	s_ashr_i32 s29, s28, 31
	v_cvt_pk_bf16_f32 v120, v132, v133
	v_lshlrev_b32_e32 v132, 16, v121
	v_and_b32_e32 v133, 0xffff0000, v121
	v_pk_add_f32 v[132:133], v[134:135], v[132:133] neg_lo:[0,1] neg_hi:[0,1]
	v_lshlrev_b32_e32 v134, 16, v244
	v_cvt_pk_bf16_f32 v121, v132, v133
	v_lshlrev_b32_e32 v132, 16, v122
	v_and_b32_e32 v133, 0xffff0000, v122
	v_pk_add_f32 v[132:133], v[230:231], v[132:133] neg_lo:[0,1] neg_hi:[0,1]
	v_and_b32_e32 v135, 0xffff0000, v244
	v_cvt_pk_bf16_f32 v122, v132, v133
	v_lshlrev_b32_e32 v132, 16, v123
	v_and_b32_e32 v133, 0xffff0000, v123
	v_pk_add_f32 v[132:133], v[180:181], v[132:133] neg_lo:[0,1] neg_hi:[0,1]
	v_lshlrev_b32_e32 v180, 16, v245
	v_cvt_pk_bf16_f32 v123, v132, v133
	global_store_dwordx4 v[218:219], v[120:123], off nt
	v_lshlrev_b32_e32 v132, 16, v243
	v_and_b32_e32 v133, 0xffff0000, v243
	v_lshlrev_b32_e32 v120, 16, v234
	v_and_b32_e32 v121, 0xffff0000, v234
	v_lshlrev_b32_e32 v122, 16, v242
	v_and_b32_e32 v123, 0xffff0000, v242
	v_pk_add_f32 v[120:121], v[120:121], v[122:123]
	v_lshlrev_b32_e32 v122, 16, v235
	v_and_b32_e32 v123, 0xffff0000, v235
	v_pk_add_f32 v[122:123], v[122:123], v[132:133]
	v_lshlrev_b32_e32 v132, 16, v236
	v_and_b32_e32 v133, 0xffff0000, v236
	v_pk_add_f32 v[132:133], v[132:133], v[134:135]
	v_pk_add_f32 v[118:119], v[118:119], v[122:123]
	v_pk_add_f32 v[116:117], v[116:117], v[120:121]
	v_pk_add_f32 v[122:123], v[112:113], v[132:133]
	v_mul_f32_e32 v112, v117, v117
	v_mul_f32_e32 v113, v119, v119
	v_lshlrev_b32_e32 v134, 16, v237
	v_and_b32_e32 v135, 0xffff0000, v237
	v_and_b32_e32 v181, 0xffff0000, v245
	v_fmac_f32_e32 v112, v116, v116
	v_fmac_f32_e32 v113, v118, v118
	v_pk_add_f32 v[134:135], v[134:135], v[180:181]
	v_add_f32_e32 v112, v112, v113
	v_mul_f32_e32 v113, v123, v123
	v_pk_add_f32 v[120:121], v[114:115], v[134:135]
	v_fmac_f32_e32 v113, v122, v122
	v_add_f32_e32 v112, v113, v112
	v_mul_f32_e32 v113, v121, v121
	v_fmac_f32_e32 v113, v120, v120
	v_add_f32_e32 v112, v113, v112
	v_add_f32_e32 v134, v203, v112
	v_cvt_pk_bf16_f32 v112, v116, v117
	v_cvt_pk_bf16_f32 v113, v118, v119
	v_cvt_pk_bf16_f32 v114, v122, v123
	v_cvt_pk_bf16_f32 v115, v120, v121
	global_store_dwordx4 v[178:179], v[112:115], off offset:1024
	v_lshlrev_b32_e32 v132, 16, v112
	v_and_b32_e32 v133, 0xffff0000, v112
	v_lshlrev_b32_e32 v112, 16, v113
	v_and_b32_e32 v113, 0xffff0000, v113
	v_pk_add_f32 v[112:113], v[118:119], v[112:113] neg_lo:[0,1] neg_hi:[0,1]
	ds_bpermute_b32 v119, v228, v134
	v_pk_add_f32 v[116:117], v[116:117], v[132:133] neg_lo:[0,1] neg_hi:[0,1]
	v_ashrrev_i32_e32 v203, 31, v202
	v_cvt_pk_bf16_f32 v116, v116, v117
	v_cvt_pk_bf16_f32 v117, v112, v113
	v_lshlrev_b32_e32 v112, 16, v114
	v_and_b32_e32 v113, 0xffff0000, v114
	v_pk_add_f32 v[112:113], v[122:123], v[112:113] neg_lo:[0,1] neg_hi:[0,1]
	v_lshlrev_b32_e32 v114, 16, v115
	v_cvt_pk_bf16_f32 v118, v112, v113
	s_waitcnt lgkmcnt(0)
	v_add_f32_e32 v112, v134, v119
	ds_bpermute_b32 v113, v227, v112
	v_and_b32_e32 v115, 0xffff0000, v115
	v_pk_add_f32 v[114:115], v[120:121], v[114:115] neg_lo:[0,1] neg_hi:[0,1]
	s_nop 0
	v_cvt_pk_bf16_f32 v119, v114, v115
	global_store_dwordx4 v[218:219], v[116:119], off offset:1024 nt
	s_and_saveexec_b64 s[2:3], s[4:5]
	v_readlane_b32 s82, v254, 12
	v_readlane_b32 s72, v253, 54
	v_readlane_b32 s83, v254, 13
	s_cbranch_execz .LBB0_398
	v_lshlrev_b64 v[114:115], 6, v[202:203]
	v_lshl_add_u64 v[114:115], s[82:83], 0, v[114:115]
	v_lshl_add_u64 v[114:115], s[28:29], 2, v[114:115]
	s_lshl_b32 s30, s57, 2
	v_lshl_add_u64 v[114:115], v[114:115], 0, s[30:31]
	s_waitcnt lgkmcnt(0)
	v_add_f32_e32 v112, v112, v113
	global_store_dword v[114:115], v112, off
